# E14: E12 + PV MFMAs issued as two back-to-back accumulator chains (o0 x4, o1 x4), same accumulation order
# speedup vs baseline: 1.0037x; 1.0027x over previous
.LBB0_731:
	s_mov_b32 s44, s29
	s_mov_b32 s28, s25
	v_add_u32_e32 v195, s45, v190
	ds_read_b64_tr_b16 v[196:197], v195 offset:24576
	ds_read_b64_tr_b16 v[198:199], v195 offset:25088
	v_add_f32_e32 v88, v68, v69
	v_add_f32_e32 v88, v70, v88
	v_add_f32_e32 v88, v71, v88
	v_add_f32_e32 v88, v72, v88
	v_add_f32_e32 v88, v73, v88
	v_cvt_pk_bf16_f32 v152, v68, v69
	v_cvt_pk_bf16_f32 v153, v70, v71
	v_mfma_f32_32x32x16_bf16 v[100:115], v[84:87], v[160:163], 0
	ds_read_b64_tr_b16 v[68:69], v195 offset:28672
	ds_read_b64_tr_b16 v[70:71], v195 offset:29184
	v_add_f32_e32 v84, v74, v88
	v_add_f32_e32 v84, v75, v84
	v_add_f32_e32 v84, v76, v84
	v_add_f32_e32 v132, v77, v84
	v_mfma_f32_32x32x16_bf16 v[84:99], v[168:171], v[160:163], 0
	v_cvt_pk_bf16_f32 v154, v72, v73
	v_cvt_pk_bf16_f32 v155, v74, v75
	ds_read_b64_tr_b16 v[72:73], v195 offset:25600
	ds_read_b64_tr_b16 v[74:75], v195 offset:26112
	v_add_f32_e32 v132, v78, v132
	v_add_f32_e32 v132, v79, v132
	v_add_f32_e32 v132, v80, v132
	v_add_f32_e32 v132, v81, v132
	v_cvt_pk_bf16_f32 v148, v76, v77
	v_cvt_pk_bf16_f32 v149, v78, v79
	v_mfma_f32_32x32x16_bf16 v[100:115], v[172:175], v[156:159], v[100:115]
	ds_read_b64_tr_b16 v[76:77], v195 offset:29696
	ds_read_b64_tr_b16 v[78:79], v195 offset:30208
	v_mfma_f32_32x32x16_bf16 v[84:99], v[164:167], v[156:159], v[84:99]
	v_add_f32_e32 v132, v82, v132
	v_add_f32_e32 v132, v83, v132
	v_add_f32_e32 v132, v52, v132
	v_add_f32_e32 v132, v53, v132
	v_cvt_pk_bf16_f32 v150, v80, v81
	v_cvt_pk_bf16_f32 v151, v82, v83
	ds_read_b64_tr_b16 v[80:81], v195 offset:26624
	ds_read_b64_tr_b16 v[82:83], v195 offset:27136
	v_mfma_f32_32x32x16_bf16 v[100:115], v[128:131], v[144:147], v[100:115]
	v_add_f32_e32 v128, v54, v132
	v_add_f32_e32 v128, v55, v128
	v_add_f32_e32 v128, v56, v128
	v_add_f32_e32 v128, v57, v128
	v_cvt_pk_bf16_f32 v140, v52, v53
	v_cvt_pk_bf16_f32 v141, v54, v55
	ds_read_b64_tr_b16 v[52:53], v195 offset:30720
	ds_read_b64_tr_b16 v[54:55], v195 offset:31232
	v_mfma_f32_32x32x16_bf16 v[84:99], v[124:127], v[144:147], v[84:99]
	v_add_f32_e32 v124, v58, v128
	v_add_f32_e32 v124, v59, v124
	v_add_f32_e32 v124, v60, v124
	v_add_f32_e32 v124, v61, v124
	v_cvt_pk_bf16_f32 v142, v56, v57
	v_cvt_pk_bf16_f32 v143, v58, v59
	ds_read_b64_tr_b16 v[56:57], v195 offset:27648
	ds_read_b64_tr_b16 v[58:59], v195 offset:28160
	v_mfma_f32_32x32x16_bf16 v[100:115], v[120:123], v[136:139], v[100:115]
	v_add_f32_e32 v120, v62, v124
	v_add_f32_e32 v120, v63, v120
	v_add_f32_e32 v120, v64, v120
	v_add_f32_e32 v120, v65, v120
	v_cvt_pk_bf16_f32 v132, v60, v61
	v_cvt_pk_bf16_f32 v133, v62, v63
	ds_read_b64_tr_b16 v[60:61], v195 offset:31744
	ds_read_b64_tr_b16 v[62:63], v195 offset:32256
	v_mfma_f32_32x32x16_bf16 v[84:99], v[116:119], v[136:139], v[84:99]
	v_add_f32_e32 v116, v66, v120
	v_add_f32_e32 v195, v67, v116
	v_cvt_pk_bf16_f32 v134, v64, v65
	v_cvt_pk_bf16_f32 v135, v66, v67
	s_add_i32 m0, s25, s59
	v_lshl_add_u64 v[64:65], v[0:1], 0, s[76:77]
	global_load_lds_dwordx4 v[64:65], off
	s_add_i32 m0, s44, s58
	v_lshl_add_u64 v[64:65], v[184:185], 0, s[34:35]
	global_load_lds_dwordx4 v[64:65], off
	s_waitcnt lgkmcnt(14)
	v_mfma_f32_32x32x16_bf16 v[4:19], v[152:155], v[196:199], v[4:19]
	v_exp_f32_e32 v100, v100
	v_exp_f32_e32 v101, v101
	v_exp_f32_e32 v102, v102
	v_exp_f32_e32 v103, v103
	s_waitcnt lgkmcnt(10)
	v_mfma_f32_32x32x16_bf16 v[4:19], v[148:151], v[72:75], v[4:19]
	v_exp_f32_e32 v104, v104
	v_exp_f32_e32 v105, v105
	v_exp_f32_e32 v106, v106
	v_exp_f32_e32 v107, v107
	v_add_u32_e32 v210, s44, v191
	ds_read_b128 v[64:67], v210
	ds_read_b128 v[120:123], v210 offset:512
	s_waitcnt lgkmcnt(8)
	v_mfma_f32_32x32x16_bf16 v[4:19], v[140:143], v[80:83], v[4:19]
	v_exp_f32_e32 v108, v108
	v_exp_f32_e32 v109, v109
	v_exp_f32_e32 v110, v110
	v_exp_f32_e32 v111, v111
	ds_read_b128 v[124:127], v210 offset:2048
	ds_read_b128 v[128:131], v210 offset:2560
	s_waitcnt lgkmcnt(6)
	v_mfma_f32_32x32x16_bf16 v[4:19], v[132:135], v[56:59], v[4:19]
	v_exp_f32_e32 v112, v112
	v_exp_f32_e32 v113, v113
	v_exp_f32_e32 v114, v114
	v_exp_f32_e32 v115, v115
	ds_read_b128 v[164:167], v210 offset:4096
	ds_read_b128 v[168:171], v210 offset:4608
	s_waitcnt lgkmcnt(8)
	v_mfma_f32_32x32x16_bf16 v[20:35], v[152:155], v[68:71], v[20:35]
	v_exp_f32_e32 v84, v84
	v_exp_f32_e32 v85, v85
	v_exp_f32_e32 v86, v86
	v_exp_f32_e32 v87, v87
	ds_read_b128 v[172:175], v210 offset:6144
	ds_read_b128 v[116:119], v210 offset:6656
	s_waitcnt lgkmcnt(8)
	v_mfma_f32_32x32x16_bf16 v[20:35], v[148:151], v[76:79], v[20:35]
	v_exp_f32_e32 v88, v88
	v_exp_f32_e32 v89, v89
	v_exp_f32_e32 v90, v90
	v_exp_f32_e32 v91, v91
	s_waitcnt lgkmcnt(8)
	v_mfma_f32_32x32x16_bf16 v[20:35], v[140:143], v[52:55], v[20:35]
	v_exp_f32_e32 v92, v92
	v_exp_f32_e32 v93, v93
	v_exp_f32_e32 v94, v94
	v_exp_f32_e32 v95, v95
	s_waitcnt lgkmcnt(8)
	v_mfma_f32_32x32x16_bf16 v[20:35], v[132:135], v[60:63], v[20:35]
	v_exp_f32_e32 v96, v96
	v_exp_f32_e32 v97, v97
	v_exp_f32_e32 v98, v98
	v_exp_f32_e32 v99, v99
	s_waitcnt vmcnt(2) lgkmcnt(0)
	s_barrier
	s_add_i32 s25, s44, 0x2000
	s_cmpk_lg_i32 s44, 0x4000
	s_cselect_b32 s25, s25, 0
	v_add_u32_e32 v200, s28, v190
	ds_read_b64_tr_b16 v[196:197], v200 offset:24576
	ds_read_b64_tr_b16 v[198:199], v200 offset:25088
	v_mfma_f32_32x32x16_bf16 v[68:83], v[64:67], v[160:163], 0
	v_add_f32_e32 v52, v100, v101
	v_add_f32_e32 v52, v102, v52
	v_add_f32_e32 v52, v103, v52
	v_add_f32_e32 v52, v104, v52
	v_add_f32_e32 v52, v105, v52
	v_cvt_pk_bf16_f32 v152, v100, v101
	v_cvt_pk_bf16_f32 v153, v102, v103
	ds_read_b64_tr_b16 v[100:101], v200 offset:28672
	ds_read_b64_tr_b16 v[102:103], v200 offset:29184
	v_add_f32_e32 v52, v106, v52
	v_add_f32_e32 v52, v107, v52
	v_add_f32_e32 v52, v108, v52
	v_add_f32_e32 v132, v109, v52
	v_mfma_f32_32x32x16_bf16 v[52:67], v[120:123], v[160:163], 0
	v_cvt_pk_bf16_f32 v154, v104, v105
	v_cvt_pk_bf16_f32 v155, v106, v107
	ds_read_b64_tr_b16 v[104:105], v200 offset:25600
	ds_read_b64_tr_b16 v[106:107], v200 offset:26112
	v_mfma_f32_32x32x16_bf16 v[68:83], v[124:127], v[156:159], v[68:83]
	v_add_f32_e32 v120, v110, v132
	v_add_f32_e32 v120, v111, v120
	v_add_f32_e32 v120, v112, v120
	v_add_f32_e32 v120, v113, v120
	v_cvt_pk_bf16_f32 v148, v108, v109
	v_cvt_pk_bf16_f32 v149, v110, v111
	ds_read_b64_tr_b16 v[108:109], v200 offset:29696
	ds_read_b64_tr_b16 v[110:111], v200 offset:30208
	v_mfma_f32_32x32x16_bf16 v[52:67], v[128:131], v[156:159], v[52:67]
	v_add_f32_e32 v120, v114, v120
	v_add_f32_e32 v120, v115, v120
	v_add_f32_e32 v120, v84, v120
	v_add_f32_e32 v120, v85, v120
	v_cvt_pk_bf16_f32 v150, v112, v113
	v_cvt_pk_bf16_f32 v151, v114, v115
	ds_read_b64_tr_b16 v[112:113], v200 offset:26624
	ds_read_b64_tr_b16 v[114:115], v200 offset:27136
	v_mfma_f32_32x32x16_bf16 v[68:83], v[164:167], v[144:147], v[68:83]
	v_add_f32_e32 v120, v86, v120
	v_add_f32_e32 v120, v87, v120
	v_add_f32_e32 v120, v88, v120
	v_add_f32_e32 v120, v89, v120
	v_cvt_pk_bf16_f32 v140, v84, v85
	v_cvt_pk_bf16_f32 v141, v86, v87
	ds_read_b64_tr_b16 v[206:207], v200 offset:30720
	ds_read_b64_tr_b16 v[208:209], v200 offset:31232
	v_mfma_f32_32x32x16_bf16 v[52:67], v[168:171], v[144:147], v[52:67]
	v_add_f32_e32 v84, v90, v120
	v_add_f32_e32 v84, v91, v84
	v_add_f32_e32 v84, v92, v84
	v_add_f32_e32 v84, v93, v84
	v_cvt_pk_bf16_f32 v142, v88, v89
	v_cvt_pk_bf16_f32 v143, v90, v91
	ds_read_b64_tr_b16 v[88:89], v200 offset:27648
	ds_read_b64_tr_b16 v[90:91], v200 offset:28160
	v_mfma_f32_32x32x16_bf16 v[68:83], v[172:175], v[136:139], v[68:83]
	v_add_f32_e32 v84, v94, v84
	v_add_f32_e32 v84, v95, v84
	v_add_f32_e32 v84, v96, v84
	v_add_f32_e32 v84, v97, v84
	v_cvt_pk_bf16_f32 v132, v92, v93
	v_cvt_pk_bf16_f32 v133, v94, v95
	ds_read_b64_tr_b16 v[92:93], v200 offset:31744
	ds_read_b64_tr_b16 v[94:95], v200 offset:32256
	v_mfma_f32_32x32x16_bf16 v[52:67], v[116:119], v[136:139], v[52:67]
	v_add_f32_e32 v84, v98, v84
	v_add_f32_e32 v200, v99, v84
	v_cvt_pk_bf16_f32 v134, v96, v97
	v_cvt_pk_bf16_f32 v135, v98, v99
	s_mov_b64 s[28:29], 0x10000
	s_add_i32 m0, s44, s59
	v_lshl_add_u64 v[84:85], v[0:1], 0, s[28:29]
	global_load_lds_dwordx4 v[84:85], off
	s_add_i32 m0, s25, s58
	v_lshl_add_u64 v[184:185], v[184:185], 0, s[36:37]
	global_load_lds_dwordx4 v[184:185], off
	s_waitcnt lgkmcnt(14)
	v_mfma_f32_32x32x16_bf16 v[4:19], v[152:155], v[196:199], v[4:19]
	v_exp_f32_e32 v68, v68
	v_exp_f32_e32 v69, v69
	v_exp_f32_e32 v70, v70
	v_exp_f32_e32 v71, v71
	s_waitcnt lgkmcnt(10)
	v_mfma_f32_32x32x16_bf16 v[4:19], v[148:151], v[104:107], v[4:19]
	v_exp_f32_e32 v72, v72
	v_exp_f32_e32 v73, v73
	v_exp_f32_e32 v74, v74
	v_exp_f32_e32 v75, v75
	v_add_u32_e32 v96, s25, v191
	ds_read_b128 v[84:87], v96
	ds_read_b128 v[168:171], v96 offset:512
	s_waitcnt lgkmcnt(8)
	v_mfma_f32_32x32x16_bf16 v[4:19], v[140:143], v[112:115], v[4:19]
	v_exp_f32_e32 v76, v76
	v_exp_f32_e32 v77, v77
	v_exp_f32_e32 v78, v78
	v_exp_f32_e32 v79, v79
	ds_read_b128 v[172:175], v96 offset:2048
	ds_read_b128 v[164:167], v96 offset:2560
	s_waitcnt lgkmcnt(6)
	v_mfma_f32_32x32x16_bf16 v[4:19], v[132:135], v[88:91], v[4:19]
	v_exp_f32_e32 v80, v80
	v_exp_f32_e32 v81, v81
	v_exp_f32_e32 v82, v82
	v_exp_f32_e32 v83, v83
	ds_read_b128 v[128:131], v96 offset:4096
	ds_read_b128 v[124:127], v96 offset:4608
	s_waitcnt lgkmcnt(8)
	v_mfma_f32_32x32x16_bf16 v[20:35], v[152:155], v[100:103], v[20:35]
	v_exp_f32_e32 v52, v52
	v_exp_f32_e32 v53, v53
	v_exp_f32_e32 v54, v54
	v_exp_f32_e32 v55, v55
	ds_read_b128 v[120:123], v96 offset:6144
	ds_read_b128 v[116:119], v96 offset:6656
	s_waitcnt lgkmcnt(8)
	v_mfma_f32_32x32x16_bf16 v[20:35], v[148:151], v[108:111], v[20:35]
	v_exp_f32_e32 v56, v56
	v_exp_f32_e32 v57, v57
	v_exp_f32_e32 v58, v58
	v_exp_f32_e32 v59, v59
	s_waitcnt lgkmcnt(8)
	v_mfma_f32_32x32x16_bf16 v[20:35], v[140:143], v[206:209], v[20:35]
	v_exp_f32_e32 v60, v60
	v_exp_f32_e32 v61, v61
	v_exp_f32_e32 v62, v62
	v_exp_f32_e32 v63, v63
	s_waitcnt lgkmcnt(8)
	v_mfma_f32_32x32x16_bf16 v[20:35], v[132:135], v[92:95], v[20:35]
	v_exp_f32_e32 v64, v64
	v_exp_f32_e32 v65, v65
	v_exp_f32_e32 v66, v66
	v_exp_f32_e32 v67, v67
	s_add_i32 s28, s25, 0x2000
	s_waitcnt vmcnt(2) lgkmcnt(0)
	s_barrier
	s_cmpk_lg_i32 s25, 0x4000
	v_add_f32_e32 v88, v192, v195
	s_cselect_b32 s29, s28, 0
	s_add_i32 s24, s24, 2
	v_add_f32_e32 v192, v88, v200
	v_lshl_add_u64 v[0:1], v[0:1], 0, s[36:37]
	s_cmpk_gt_u32 s24, 0xf8
	s_mov_b32 s45, s44
	s_cbranch_scc0 .LBB0_731
	s_and_b32 s24, s60, 0x3fffffc0
	s_cmp_lg_u32 0, -1
	s_cselect_b32 s28, 0, 0
	s_addk_i32 s28, 0x6000
	s_lshl_b32 s24, s24, 2
	v_add3_u32 v0, v194, s28, v193
	s_add_i32 s28, s24, 0
	v_add_u32_e32 v1, s44, v190
	ds_read_b64_tr_b16 v[194:195], v1 offset:24576
	ds_read_b64_tr_b16 v[196:197], v1 offset:25088
	v_add_f32_e32 v88, v68, v69
	v_add_f32_e32 v88, v70, v88
	v_add_f32_e32 v88, v71, v88
	v_add_f32_e32 v88, v72, v88
	v_add_f32_e32 v88, v73, v88
	v_cvt_pk_bf16_f32 v152, v68, v69
	v_cvt_pk_bf16_f32 v153, v70, v71
	s_waitcnt lgkmcnt(9)
	v_mfma_f32_32x32x16_bf16 v[100:115], v[84:87], v[160:163], v[36:51]
	ds_read_b64_tr_b16 v[68:69], v1 offset:28672
	ds_read_b64_tr_b16 v[70:71], v1 offset:29184
	v_add_f32_e32 v84, v74, v88
	v_add_f32_e32 v84, v75, v84
	v_add_f32_e32 v84, v76, v84
	v_add_f32_e32 v132, v77, v84
	v_cvt_pk_bf16_f32 v154, v72, v73
	v_cvt_pk_bf16_f32 v155, v74, v75
	s_waitcnt lgkmcnt(10)
	v_mfma_f32_32x32x16_bf16 v[84:99], v[168:171], v[160:163], v[36:51]
	ds_read_b64_tr_b16 v[72:73], v1 offset:25600
	ds_read_b64_tr_b16 v[74:75], v1 offset:26112
	v_add_f32_e32 v132, v78, v132
	v_add_f32_e32 v132, v79, v132
	v_add_f32_e32 v132, v80, v132
	v_add_f32_e32 v132, v81, v132
	v_cvt_pk_bf16_f32 v148, v76, v77
	v_cvt_pk_bf16_f32 v149, v78, v79
	s_waitcnt lgkmcnt(11)
	v_mfma_f32_32x32x16_bf16 v[100:115], v[172:175], v[156:159], v[100:115]
	ds_read_b64_tr_b16 v[76:77], v1 offset:29696
	ds_read_b64_tr_b16 v[78:79], v1 offset:30208
	v_add_f32_e32 v132, v82, v132
	v_add_f32_e32 v132, v83, v132
	v_add_f32_e32 v132, v52, v132
	v_add_f32_e32 v132, v53, v132
	v_cvt_pk_bf16_f32 v150, v80, v81
	v_cvt_pk_bf16_f32 v151, v82, v83
	s_waitcnt lgkmcnt(12)
	v_mfma_f32_32x32x16_bf16 v[84:99], v[164:167], v[156:159], v[84:99]
	ds_read_b64_tr_b16 v[80:81], v1 offset:26624
	ds_read_b64_tr_b16 v[82:83], v1 offset:27136
	s_waitcnt lgkmcnt(13)
	v_mfma_f32_32x32x16_bf16 v[100:115], v[128:131], v[144:147], v[100:115]
	v_add_f32_e32 v128, v54, v132
	v_add_f32_e32 v128, v55, v128
	v_add_f32_e32 v128, v56, v128
	v_add_f32_e32 v128, v57, v128
	v_cvt_pk_bf16_f32 v140, v52, v53
	v_cvt_pk_bf16_f32 v141, v54, v55
	ds_read_b64_tr_b16 v[52:53], v1 offset:30720
	ds_read_b64_tr_b16 v[54:55], v1 offset:31232
	s_waitcnt lgkmcnt(14)
	v_mfma_f32_32x32x16_bf16 v[84:99], v[124:127], v[144:147], v[84:99]
	v_add_f32_e32 v124, v58, v128
	v_add_f32_e32 v124, v59, v124
	v_add_f32_e32 v124, v60, v124
	v_add_f32_e32 v124, v61, v124
	v_cvt_pk_bf16_f32 v142, v56, v57
	v_cvt_pk_bf16_f32 v143, v58, v59
	ds_read_b64_tr_b16 v[56:57], v1 offset:27648
	ds_read_b64_tr_b16 v[58:59], v1 offset:28160
	s_waitcnt lgkmcnt(14)
	v_mfma_f32_32x32x16_bf16 v[100:115], v[120:123], v[136:139], v[100:115]
	v_add_f32_e32 v120, v62, v124
	v_add_f32_e32 v120, v63, v120
	v_add_f32_e32 v120, v64, v120
	v_add_f32_e32 v120, v65, v120
	v_cvt_pk_bf16_f32 v132, v60, v61
	v_cvt_pk_bf16_f32 v133, v62, v63
	ds_read_b64_tr_b16 v[60:61], v1 offset:31744
	ds_read_b64_tr_b16 v[62:63], v1 offset:32256
	v_add_f32_e32 v1, v66, v120
	v_add_f32_e32 v1, v67, v1
	v_add_f32_e32 v1, 0, v1
	v_cvt_pk_bf16_f32 v134, v64, v65
	v_cvt_pk_bf16_f32 v135, v66, v67
	v_mfma_f32_32x32x16_bf16 v[84:99], v[116:119], v[136:139], v[84:99]
	s_mov_b64 s[46:47], 0x3f8000
	s_add_i32 s24, s25, s59
	v_lshl_add_u64 v[64:65], v[182:183], 0, s[46:47]
	s_mov_b32 s44, m0
	s_mov_b32 m0, s24
	s_nop 0
	global_load_lds_dwordx4 v[64:65], off
	s_mov_b32 m0, s44
	s_mov_b64 s[44:45], 0x3f0000
	v_lshl_add_u64 v[64:65], v[180:181], 0, s[44:45]
	s_add_i32 s24, s29, s58
	s_mov_b32 s44, m0
	s_mov_b32 m0, s24
	s_nop 0
	global_load_lds_dwordx4 v[64:65], off
	s_mov_b32 m0, s44
	v_add_f32_e32 v1, v192, v1
	s_waitcnt lgkmcnt(14)
	v_mfma_f32_32x32x16_bf16 v[4:19], v[152:155], v[194:197], v[4:19]
	v_exp_f32_e32 v100, v100
	v_exp_f32_e32 v101, v101
	v_exp_f32_e32 v102, v102
	v_exp_f32_e32 v103, v103
	s_waitcnt lgkmcnt(12)
	v_mfma_f32_32x32x16_bf16 v[20:35], v[152:155], v[68:71], v[20:35]
	v_exp_f32_e32 v104, v104
	v_exp_f32_e32 v105, v105
	v_exp_f32_e32 v106, v106
	v_exp_f32_e32 v107, v107
	v_add_u32_e32 v68, s29, v191
	ds_read_b128 v[64:67], v68
	ds_read_b128 v[164:167], v68 offset:512
	s_waitcnt lgkmcnt(12)
	v_mfma_f32_32x32x16_bf16 v[4:19], v[148:151], v[72:75], v[4:19]
	v_exp_f32_e32 v108, v108
	v_exp_f32_e32 v109, v109
	v_exp_f32_e32 v110, v110
	v_exp_f32_e32 v111, v111
	ds_read_b128 v[72:75], v68 offset:2048
	ds_read_b128 v[168:171], v68 offset:2560
	s_waitcnt lgkmcnt(12)
	v_mfma_f32_32x32x16_bf16 v[20:35], v[148:151], v[76:79], v[20:35]
	v_exp_f32_e32 v112, v112
	v_exp_f32_e32 v113, v113
	v_exp_f32_e32 v114, v114
	v_exp_f32_e32 v115, v115
	ds_read_b128 v[76:79], v68 offset:4096
	ds_read_b128 v[172:175], v68 offset:4608
	s_waitcnt lgkmcnt(12)
	v_mfma_f32_32x32x16_bf16 v[4:19], v[140:143], v[80:83], v[4:19]
	v_exp_f32_e32 v84, v84
	v_exp_f32_e32 v85, v85
	v_exp_f32_e32 v86, v86
	v_exp_f32_e32 v87, v87
	ds_read_b128 v[80:83], v68 offset:6144
	ds_read_b128 v[68:71], v68 offset:6656
	s_waitcnt lgkmcnt(12)
	v_mfma_f32_32x32x16_bf16 v[20:35], v[140:143], v[52:55], v[20:35]
	v_exp_f32_e32 v88, v88
	v_exp_f32_e32 v89, v89
	v_exp_f32_e32 v90, v90
	v_exp_f32_e32 v91, v91
	s_waitcnt lgkmcnt(10)
	v_mfma_f32_32x32x16_bf16 v[4:19], v[132:135], v[56:59], v[4:19]
	v_exp_f32_e32 v92, v92
	v_exp_f32_e32 v93, v93
	v_exp_f32_e32 v94, v94
	v_exp_f32_e32 v95, v95
	s_waitcnt lgkmcnt(8)
	v_mfma_f32_32x32x16_bf16 v[20:35], v[132:135], v[60:63], v[20:35]
	v_exp_f32_e32 v96, v96
	v_exp_f32_e32 v97, v97
	v_exp_f32_e32 v98, v98
	v_exp_f32_e32 v99, v99
	s_waitcnt vmcnt(2) lgkmcnt(0)
	s_barrier
	s_add_i32 s24, s29, 0x2000
	s_cmpk_lg_i32 s29, 0x4000
	s_cselect_b32 s44, s24, 0
	v_add_u32_e32 v184, s25, v190
	ds_read_b64_tr_b16 v[192:193], v184 offset:24576
	ds_read_b64_tr_b16 v[194:195], v184 offset:25088
	v_add_f32_e32 v52, v100, v101
	v_add_f32_e32 v52, v102, v52
	v_add_f32_e32 v52, v103, v52
	v_add_f32_e32 v52, v104, v52
	v_add_f32_e32 v52, v105, v52
	v_cvt_pk_bf16_f32 v152, v100, v101
	v_cvt_pk_bf16_f32 v153, v102, v103
	s_waitcnt lgkmcnt(9)
	v_mfma_f32_32x32x16_bf16 v[116:131], v[64:67], v[160:163], v[36:51]
	ds_read_b64_tr_b16 v[100:101], v184 offset:28672
	ds_read_b64_tr_b16 v[102:103], v184 offset:29184
	v_add_f32_e32 v52, v106, v52
	v_add_f32_e32 v52, v107, v52
	v_add_f32_e32 v52, v108, v52
	v_add_f32_e32 v132, v109, v52
	v_cvt_pk_bf16_f32 v154, v104, v105
	v_cvt_pk_bf16_f32 v155, v106, v107
	s_waitcnt lgkmcnt(10)
	v_mfma_f32_32x32x16_bf16 v[52:67], v[164:167], v[160:163], v[36:51]
	ds_read_b64_tr_b16 v[104:105], v184 offset:25600
	ds_read_b64_tr_b16 v[106:107], v184 offset:26112
	s_waitcnt lgkmcnt(11)
	v_mfma_f32_32x32x16_bf16 v[116:131], v[72:75], v[156:159], v[116:131]
	v_add_f32_e32 v72, v110, v132
	v_add_f32_e32 v72, v111, v72
	v_add_f32_e32 v72, v112, v72
	v_add_f32_e32 v132, v113, v72
	v_cvt_pk_bf16_f32 v148, v108, v109
	v_cvt_pk_bf16_f32 v149, v110, v111
	ds_read_b64_tr_b16 v[72:73], v184 offset:29696
	ds_read_b64_tr_b16 v[74:75], v184 offset:30208
	v_add_f32_e32 v108, v114, v132
	v_add_f32_e32 v108, v115, v108
	v_add_f32_e32 v108, v84, v108
	v_add_f32_e32 v132, v85, v108
	v_cvt_pk_bf16_f32 v150, v112, v113
	v_cvt_pk_bf16_f32 v151, v114, v115
	s_waitcnt lgkmcnt(12)
	v_mfma_f32_32x32x16_bf16 v[52:67], v[168:171], v[156:159], v[52:67]
	ds_read_b64_tr_b16 v[108:109], v184 offset:26624
	ds_read_b64_tr_b16 v[110:111], v184 offset:27136
	s_waitcnt lgkmcnt(13)
	v_mfma_f32_32x32x16_bf16 v[116:131], v[76:79], v[144:147], v[116:131]
	v_add_f32_e32 v76, v86, v132
	v_add_f32_e32 v76, v87, v76
	v_add_f32_e32 v76, v88, v76
	v_add_f32_e32 v112, v89, v76
	v_cvt_pk_bf16_f32 v140, v84, v85
	v_cvt_pk_bf16_f32 v141, v86, v87
	ds_read_b64_tr_b16 v[76:77], v184 offset:30720
	ds_read_b64_tr_b16 v[78:79], v184 offset:31232
	v_add_f32_e32 v84, v90, v112
	v_add_f32_e32 v84, v91, v84
	v_add_f32_e32 v84, v92, v84
	v_add_f32_e32 v84, v93, v84
	v_cvt_pk_bf16_f32 v142, v88, v89
	v_cvt_pk_bf16_f32 v143, v90, v91
	s_waitcnt lgkmcnt(14)
	v_mfma_f32_32x32x16_bf16 v[52:67], v[172:175], v[144:147], v[52:67]
	ds_read_b64_tr_b16 v[88:89], v184 offset:27648
	ds_read_b64_tr_b16 v[90:91], v184 offset:28160
	s_waitcnt lgkmcnt(14)
	v_mfma_f32_32x32x16_bf16 v[116:131], v[80:83], v[136:139], v[116:131]
	v_add_f32_e32 v80, v94, v84
	v_add_f32_e32 v80, v95, v80
	v_add_f32_e32 v80, v96, v80
	v_add_f32_e32 v84, v97, v80
	v_cvt_pk_bf16_f32 v132, v92, v93
	v_cvt_pk_bf16_f32 v133, v94, v95
	ds_read_b64_tr_b16 v[80:81], v184 offset:31744
	ds_read_b64_tr_b16 v[82:83], v184 offset:32256
	v_mfma_f32_32x32x16_bf16 v[52:67], v[68:71], v[136:139], v[52:67]
	v_add_f32_e32 v68, v98, v84
	v_add_f32_e32 v68, v99, v68
	v_add_f32_e32 v68, 0, v68
	v_cvt_pk_bf16_f32 v134, v96, v97
	v_cvt_pk_bf16_f32 v135, v98, v99
	s_mov_b64 s[60:61], 0x3fc000
	v_add_f32_e32 v1, v1, v68
	s_add_i32 s24, s29, s59
	v_lshl_add_u64 v[68:69], v[182:183], 0, s[60:61]
	s_mov_b32 s25, m0
	s_mov_b32 m0, s24
	s_nop 0
	global_load_lds_dwordx4 v[68:69], off
	s_mov_b32 m0, s25
	s_mov_b64 s[24:25], 0x3f4000
	s_add_i32 s45, s44, s58
	v_lshl_add_u64 v[68:69], v[180:181], 0, s[24:25]
	s_mov_b32 s24, m0
	s_mov_b32 m0, s45
	s_nop 0
	global_load_lds_dwordx4 v[68:69], off
	s_mov_b32 m0, s24
	s_waitcnt lgkmcnt(14)
	v_mfma_f32_32x32x16_bf16 v[4:19], v[152:155], v[192:195], v[4:19]
	v_exp_f32_e32 v116, v116
	v_exp_f32_e32 v117, v117
	v_exp_f32_e32 v118, v118
	v_exp_f32_e32 v119, v119
	s_waitcnt lgkmcnt(12)
	v_mfma_f32_32x32x16_bf16 v[20:35], v[152:155], v[100:103], v[20:35]
	v_exp_f32_e32 v120, v120
	v_exp_f32_e32 v121, v121
	v_exp_f32_e32 v122, v122
	v_exp_f32_e32 v123, v123
	v_add_u32_e32 v84, s44, v191
	ds_read_b128 v[68:71], v84
	ds_read_b128 v[92:95], v84 offset:512
	s_waitcnt lgkmcnt(12)
	v_mfma_f32_32x32x16_bf16 v[4:19], v[148:151], v[104:107], v[4:19]
	v_exp_f32_e32 v124, v124
	v_exp_f32_e32 v125, v125
	v_exp_f32_e32 v126, v126
	v_exp_f32_e32 v127, v127
	ds_read_b128 v[96:99], v84 offset:2048
	ds_read_b128 v[164:167], v84 offset:2560
	s_waitcnt lgkmcnt(12)
	v_mfma_f32_32x32x16_bf16 v[20:35], v[148:151], v[72:75], v[20:35]
	v_exp_f32_e32 v128, v128
	v_exp_f32_e32 v129, v129
	v_exp_f32_e32 v130, v130
	v_exp_f32_e32 v131, v131
	ds_read_b128 v[168:171], v84 offset:4096
	ds_read_b128 v[172:175], v84 offset:4608
	s_waitcnt lgkmcnt(12)
	v_mfma_f32_32x32x16_bf16 v[4:19], v[140:143], v[108:111], v[4:19]
	v_exp_f32_e32 v52, v52
	v_exp_f32_e32 v53, v53
	v_exp_f32_e32 v54, v54
	v_exp_f32_e32 v55, v55
	ds_read_b128 v[182:185], v84 offset:6144
	ds_read_b128 v[84:87], v84 offset:6656
	s_waitcnt lgkmcnt(12)
	v_mfma_f32_32x32x16_bf16 v[20:35], v[140:143], v[76:79], v[20:35]
	v_exp_f32_e32 v56, v56
	v_exp_f32_e32 v57, v57
	v_exp_f32_e32 v58, v58
	v_exp_f32_e32 v59, v59
	s_waitcnt lgkmcnt(10)
	v_mfma_f32_32x32x16_bf16 v[4:19], v[132:135], v[88:91], v[4:19]
	v_exp_f32_e32 v60, v60
	v_exp_f32_e32 v61, v61
	v_exp_f32_e32 v62, v62
	v_exp_f32_e32 v63, v63
	s_waitcnt lgkmcnt(8)
	v_mfma_f32_32x32x16_bf16 v[20:35], v[132:135], v[80:83], v[20:35]
	v_exp_f32_e32 v64, v64
	v_exp_f32_e32 v65, v65
	v_exp_f32_e32 v66, v66
	v_exp_f32_e32 v67, v67
	s_waitcnt vmcnt(2) lgkmcnt(0)
	s_barrier
	s_add_i32 s24, s44, 0x2000
	s_cmpk_lg_i32 s44, 0x4000
	s_cselect_b32 s25, s24, 0
	v_add_u32_e32 v192, s29, v190
	ds_read_b64_tr_b16 v[88:89], v192 offset:24576
	ds_read_b64_tr_b16 v[90:91], v192 offset:25088
	v_add_f32_e32 v72, v116, v117
	v_add_f32_e32 v72, v118, v72
	v_add_f32_e32 v72, v119, v72
	v_add_f32_e32 v72, v120, v72
	v_add_f32_e32 v72, v121, v72
	v_cvt_pk_bf16_f32 v152, v116, v117
	v_cvt_pk_bf16_f32 v153, v118, v119
	s_waitcnt lgkmcnt(9)
	v_mfma_f32_32x32x16_bf16 v[100:115], v[68:71], v[160:163], v[36:51]
	ds_read_b64_tr_b16 v[116:117], v192 offset:28672
	ds_read_b64_tr_b16 v[118:119], v192 offset:29184
	v_add_f32_e32 v68, v122, v72
	v_add_f32_e32 v68, v123, v68
	v_add_f32_e32 v68, v124, v68
	v_add_f32_e32 v132, v125, v68
	v_cvt_pk_bf16_f32 v154, v120, v121
	v_cvt_pk_bf16_f32 v155, v122, v123
	s_waitcnt lgkmcnt(10)
	v_mfma_f32_32x32x16_bf16 v[68:83], v[92:95], v[160:163], v[36:51]
	ds_read_b64_tr_b16 v[92:93], v192 offset:25600
	ds_read_b64_tr_b16 v[94:95], v192 offset:26112
	s_waitcnt lgkmcnt(11)
	v_mfma_f32_32x32x16_bf16 v[100:115], v[96:99], v[156:159], v[100:115]
	v_add_f32_e32 v96, v126, v132
	v_add_f32_e32 v96, v127, v96
	v_add_f32_e32 v96, v128, v96
	v_add_f32_e32 v120, v129, v96
	v_cvt_pk_bf16_f32 v148, v124, v125
	v_cvt_pk_bf16_f32 v149, v126, v127
	ds_read_b64_tr_b16 v[96:97], v192 offset:29696
	ds_read_b64_tr_b16 v[98:99], v192 offset:30208
	v_add_f32_e32 v120, v130, v120
	v_add_f32_e32 v120, v131, v120
	v_add_f32_e32 v120, v52, v120
	v_add_f32_e32 v124, v53, v120
	v_cvt_pk_bf16_f32 v150, v128, v129
	v_cvt_pk_bf16_f32 v151, v130, v131
	s_waitcnt lgkmcnt(12)
	v_mfma_f32_32x32x16_bf16 v[68:83], v[164:167], v[156:159], v[68:83]
	ds_read_b64_tr_b16 v[120:121], v192 offset:26624
	ds_read_b64_tr_b16 v[122:123], v192 offset:27136
	v_add_f32_e32 v124, v54, v124
	v_add_f32_e32 v124, v55, v124
	v_add_f32_e32 v124, v56, v124
	v_add_f32_e32 v124, v57, v124
	v_cvt_pk_bf16_f32 v140, v52, v53
	v_cvt_pk_bf16_f32 v141, v54, v55
	s_waitcnt lgkmcnt(13)
	v_mfma_f32_32x32x16_bf16 v[100:115], v[168:171], v[144:147], v[100:115]
	ds_read_b64_tr_b16 v[52:53], v192 offset:30720
	ds_read_b64_tr_b16 v[54:55], v192 offset:31232
	v_add_f32_e32 v124, v58, v124
	v_add_f32_e32 v124, v59, v124
	v_add_f32_e32 v124, v60, v124
	v_add_f32_e32 v124, v61, v124
	v_cvt_pk_bf16_f32 v142, v56, v57
	v_cvt_pk_bf16_f32 v143, v58, v59
	s_waitcnt lgkmcnt(14)
	v_mfma_f32_32x32x16_bf16 v[68:83], v[172:175], v[144:147], v[68:83]
	ds_read_b64_tr_b16 v[56:57], v192 offset:27648
	ds_read_b64_tr_b16 v[58:59], v192 offset:28160
	v_add_f32_e32 v124, v62, v124
	v_add_f32_e32 v124, v63, v124
	v_add_f32_e32 v124, v64, v124
	v_add_f32_e32 v124, v65, v124
	v_cvt_pk_bf16_f32 v132, v60, v61
	v_cvt_pk_bf16_f32 v133, v62, v63
	s_waitcnt lgkmcnt(14)
	v_mfma_f32_32x32x16_bf16 v[100:115], v[182:185], v[136:139], v[100:115]
	ds_read_b64_tr_b16 v[60:61], v192 offset:31744
	ds_read_b64_tr_b16 v[62:63], v192 offset:32256
	v_mfma_f32_32x32x16_bf16 v[68:83], v[84:87], v[136:139], v[68:83]
	v_add_f32_e32 v84, v66, v124
	v_add_f32_e32 v84, v67, v84
	v_add_f32_e32 v84, 0, v84
	v_cvt_pk_bf16_f32 v134, v64, v65
	v_cvt_pk_bf16_f32 v135, v66, v67
	v_lshl_add_u64 v[64:65], v[180:181], 0, s[46:47]
	s_add_i32 s24, s25, s58
	s_mov_b32 s29, m0
	s_mov_b32 m0, s24
	s_nop 0
	global_load_lds_dwordx4 v[64:65], off
	s_mov_b32 m0, s29
	v_add_f32_e32 v1, v1, v84
	s_waitcnt lgkmcnt(14)
	v_mfma_f32_32x32x16_bf16 v[4:19], v[152:155], v[88:91], v[4:19]
	v_exp_f32_e32 v100, v100
	v_exp_f32_e32 v101, v101
	v_exp_f32_e32 v102, v102
	v_exp_f32_e32 v103, v103
	s_waitcnt lgkmcnt(12)
	v_mfma_f32_32x32x16_bf16 v[20:35], v[152:155], v[116:119], v[20:35]
	v_exp_f32_e32 v104, v104
	v_exp_f32_e32 v105, v105
	v_exp_f32_e32 v106, v106
	v_exp_f32_e32 v107, v107
	v_add_u32_e32 v84, s25, v191
	ds_read_b128 v[64:67], v84
	ds_read_b128 v[124:127], v84 offset:512
	s_waitcnt lgkmcnt(12)
	v_mfma_f32_32x32x16_bf16 v[4:19], v[148:151], v[92:95], v[4:19]
	v_exp_f32_e32 v108, v108
	v_exp_f32_e32 v109, v109
	v_exp_f32_e32 v110, v110
	v_exp_f32_e32 v111, v111
	ds_read_b128 v[128:131], v84 offset:2048
	ds_read_b128 v[164:167], v84 offset:2560
	s_waitcnt lgkmcnt(12)
	v_mfma_f32_32x32x16_bf16 v[20:35], v[148:151], v[96:99], v[20:35]
	v_exp_f32_e32 v112, v112
	v_exp_f32_e32 v113, v113
	v_exp_f32_e32 v114, v114
	v_exp_f32_e32 v115, v115
	ds_read_b128 v[168:171], v84 offset:4096
	ds_read_b128 v[172:175], v84 offset:4608
	s_waitcnt lgkmcnt(12)
	v_mfma_f32_32x32x16_bf16 v[4:19], v[140:143], v[120:123], v[4:19]
	v_exp_f32_e32 v68, v68
	v_exp_f32_e32 v69, v69
	v_exp_f32_e32 v70, v70
	v_exp_f32_e32 v71, v71
	ds_read_b128 v[120:123], v84 offset:6144
	ds_read_b128 v[116:119], v84 offset:6656
	s_waitcnt lgkmcnt(12)
	v_mfma_f32_32x32x16_bf16 v[20:35], v[140:143], v[52:55], v[20:35]
	v_exp_f32_e32 v72, v72
	v_exp_f32_e32 v73, v73
	v_exp_f32_e32 v74, v74
	v_exp_f32_e32 v75, v75
	s_waitcnt lgkmcnt(10)
	v_mfma_f32_32x32x16_bf16 v[4:19], v[132:135], v[56:59], v[4:19]
	v_exp_f32_e32 v76, v76
	v_exp_f32_e32 v77, v77
	v_exp_f32_e32 v78, v78
	v_exp_f32_e32 v79, v79
	s_waitcnt lgkmcnt(8)
	v_mfma_f32_32x32x16_bf16 v[20:35], v[132:135], v[60:63], v[20:35]
	v_exp_f32_e32 v80, v80
	v_exp_f32_e32 v81, v81
	v_exp_f32_e32 v82, v82
	v_exp_f32_e32 v83, v83
	s_waitcnt vmcnt(1) lgkmcnt(0)
	s_barrier
	s_add_i32 s24, s25, 0x2000
	s_cmpk_lg_i32 s25, 0x4000
	s_cselect_b32 s24, s24, 0
	v_add_u32_e32 v192, s44, v190
	ds_read_b64_tr_b16 v[182:183], v192 offset:24576
	ds_read_b64_tr_b16 v[184:185], v192 offset:25088
	v_add_f32_e32 v52, v100, v101
	v_add_f32_e32 v52, v102, v52
	v_add_f32_e32 v52, v103, v52
	v_add_f32_e32 v52, v104, v52
	v_add_f32_e32 v52, v105, v52
	v_cvt_pk_bf16_f32 v152, v100, v101
	v_cvt_pk_bf16_f32 v153, v102, v103
	s_waitcnt lgkmcnt(9)
	v_mfma_f32_32x32x16_bf16 v[84:99], v[64:67], v[160:163], v[36:51]
	ds_read_b64_tr_b16 v[100:101], v192 offset:28672
	ds_read_b64_tr_b16 v[102:103], v192 offset:29184
	v_add_f32_e32 v52, v106, v52
	v_add_f32_e32 v52, v107, v52
	v_add_f32_e32 v52, v108, v52
	v_add_f32_e32 v132, v109, v52
	v_cvt_pk_bf16_f32 v154, v104, v105
	v_cvt_pk_bf16_f32 v155, v106, v107
	s_waitcnt lgkmcnt(10)
	v_mfma_f32_32x32x16_bf16 v[52:67], v[124:127], v[160:163], v[36:51]
	ds_read_b64_tr_b16 v[104:105], v192 offset:25600
	ds_read_b64_tr_b16 v[106:107], v192 offset:26112
	v_add_f32_e32 v124, v110, v132
	v_add_f32_e32 v124, v111, v124
	v_add_f32_e32 v124, v112, v124
	v_add_f32_e32 v124, v113, v124
	v_cvt_pk_bf16_f32 v148, v108, v109
	v_cvt_pk_bf16_f32 v149, v110, v111
	s_waitcnt lgkmcnt(11)
	v_mfma_f32_32x32x16_bf16 v[84:99], v[128:131], v[156:159], v[84:99]
	ds_read_b64_tr_b16 v[108:109], v192 offset:29696
	ds_read_b64_tr_b16 v[110:111], v192 offset:30208
	v_add_f32_e32 v124, v114, v124
	v_add_f32_e32 v124, v115, v124
	v_add_f32_e32 v124, v68, v124
	v_add_f32_e32 v124, v69, v124
	v_cvt_pk_bf16_f32 v150, v112, v113
	v_cvt_pk_bf16_f32 v151, v114, v115
	s_waitcnt lgkmcnt(12)
	v_mfma_f32_32x32x16_bf16 v[52:67], v[164:167], v[156:159], v[52:67]
	ds_read_b64_tr_b16 v[112:113], v192 offset:26624
	ds_read_b64_tr_b16 v[114:115], v192 offset:27136
	v_add_f32_e32 v124, v70, v124
	v_add_f32_e32 v124, v71, v124
	v_add_f32_e32 v124, v72, v124
	v_add_f32_e32 v124, v73, v124
	v_cvt_pk_bf16_f32 v140, v68, v69
	v_cvt_pk_bf16_f32 v141, v70, v71
	s_waitcnt lgkmcnt(13)
	v_mfma_f32_32x32x16_bf16 v[84:99], v[168:171], v[144:147], v[84:99]
	ds_read_b64_tr_b16 v[68:69], v192 offset:30720
	ds_read_b64_tr_b16 v[70:71], v192 offset:31232
	v_add_f32_e32 v124, v74, v124
	v_add_f32_e32 v124, v75, v124
	v_add_f32_e32 v124, v76, v124
	v_add_f32_e32 v124, v77, v124
	v_cvt_pk_bf16_f32 v142, v72, v73
	v_cvt_pk_bf16_f32 v143, v74, v75
	s_waitcnt lgkmcnt(14)
	v_mfma_f32_32x32x16_bf16 v[52:67], v[172:175], v[144:147], v[52:67]
	ds_read_b64_tr_b16 v[72:73], v192 offset:27648
	ds_read_b64_tr_b16 v[74:75], v192 offset:28160
	s_waitcnt lgkmcnt(14)
	v_mfma_f32_32x32x16_bf16 v[84:99], v[120:123], v[136:139], v[84:99]
	v_add_f32_e32 v120, v78, v124
	v_add_f32_e32 v120, v79, v120
	v_add_f32_e32 v120, v80, v120
	v_add_f32_e32 v120, v81, v120
	v_cvt_pk_bf16_f32 v132, v76, v77
	v_cvt_pk_bf16_f32 v133, v78, v79
	ds_read_b64_tr_b16 v[76:77], v192 offset:31744
	ds_read_b64_tr_b16 v[78:79], v192 offset:32256
	v_mfma_f32_32x32x16_bf16 v[52:67], v[116:119], v[136:139], v[52:67]
	v_add_f32_e32 v116, v82, v120
	v_add_f32_e32 v116, v83, v116
	v_add_f32_e32 v116, 0, v116
	v_cvt_pk_bf16_f32 v134, v80, v81
	v_cvt_pk_bf16_f32 v135, v82, v83
	s_add_i32 s29, s24, s58
	v_lshl_add_u64 v[80:81], v[180:181], 0, s[60:61]
	s_mov_b32 s44, m0
	s_mov_b32 m0, s29
	s_nop 0
	global_load_lds_dwordx4 v[80:81], off
	s_mov_b32 m0, s44
	v_add_f32_e32 v1, v1, v116
	s_waitcnt lgkmcnt(14)
	v_mfma_f32_32x32x16_bf16 v[4:19], v[152:155], v[182:185], v[4:19]
	v_exp_f32_e32 v84, v84
	v_exp_f32_e32 v85, v85
	v_exp_f32_e32 v86, v86
	v_exp_f32_e32 v87, v87
	s_waitcnt lgkmcnt(12)
	v_mfma_f32_32x32x16_bf16 v[20:35], v[152:155], v[100:103], v[20:35]
	v_exp_f32_e32 v88, v88
	v_exp_f32_e32 v89, v89
	v_exp_f32_e32 v90, v90
	v_exp_f32_e32 v91, v91
	v_add_u32_e32 v80, s24, v191
	ds_read_b128 v[116:119], v80
	ds_read_b128 v[120:123], v80 offset:512
	s_waitcnt lgkmcnt(12)
	v_mfma_f32_32x32x16_bf16 v[4:19], v[148:151], v[104:107], v[4:19]
	v_exp_f32_e32 v92, v92
	v_exp_f32_e32 v93, v93
	v_exp_f32_e32 v94, v94
	v_exp_f32_e32 v95, v95
	ds_read_b128 v[104:107], v80 offset:2048
	ds_read_b128 v[124:127], v80 offset:2560
	s_waitcnt lgkmcnt(12)
	v_mfma_f32_32x32x16_bf16 v[20:35], v[148:151], v[108:111], v[20:35]
	v_exp_f32_e32 v96, v96
	v_exp_f32_e32 v97, v97
	v_exp_f32_e32 v98, v98
	v_exp_f32_e32 v99, v99
	ds_read_b128 v[108:111], v80 offset:4096
	ds_read_b128 v[128:131], v80 offset:4608
	s_waitcnt lgkmcnt(12)
	v_mfma_f32_32x32x16_bf16 v[4:19], v[140:143], v[112:115], v[4:19]
	v_exp_f32_e32 v52, v52
	v_exp_f32_e32 v53, v53
	v_exp_f32_e32 v54, v54
	v_exp_f32_e32 v55, v55
	ds_read_b128 v[112:115], v80 offset:6144
	ds_read_b128 v[100:103], v80 offset:6656
	s_waitcnt lgkmcnt(12)
	v_mfma_f32_32x32x16_bf16 v[20:35], v[140:143], v[68:71], v[20:35]
	v_exp_f32_e32 v56, v56
	v_exp_f32_e32 v57, v57
	v_exp_f32_e32 v58, v58
	v_exp_f32_e32 v59, v59
	s_waitcnt lgkmcnt(10)
	v_mfma_f32_32x32x16_bf16 v[4:19], v[132:135], v[72:75], v[4:19]
	v_exp_f32_e32 v60, v60
	v_exp_f32_e32 v61, v61
	v_exp_f32_e32 v62, v62
	v_exp_f32_e32 v63, v63
	s_waitcnt lgkmcnt(8)
	v_mfma_f32_32x32x16_bf16 v[20:35], v[132:135], v[76:79], v[20:35]
	v_exp_f32_e32 v64, v64
	v_exp_f32_e32 v65, v65
	v_exp_f32_e32 v66, v66
	v_exp_f32_e32 v67, v67
	s_waitcnt vmcnt(0) lgkmcnt(0)
	s_barrier
	v_add_u32_e32 v168, s25, v190
	ds_read_b64_tr_b16 v[164:165], v168 offset:24576
	ds_read_b64_tr_b16 v[166:167], v168 offset:25088
	v_add_f32_e32 v68, v84, v85
	v_add_f32_e32 v68, v86, v68
	v_add_f32_e32 v68, v87, v68
	v_add_f32_e32 v68, v88, v68
	v_add_f32_e32 v132, v89, v68
	v_cvt_pk_bf16_f32 v152, v84, v85
	v_cvt_pk_bf16_f32 v153, v86, v87
	s_waitcnt lgkmcnt(9)
	v_mfma_f32_32x32x16_bf16 v[68:83], v[116:119], v[160:163], v[36:51]
	ds_read_b64_tr_b16 v[84:85], v168 offset:28672
	ds_read_b64_tr_b16 v[86:87], v168 offset:29184
	v_add_f32_e32 v116, v90, v132
	v_add_f32_e32 v116, v91, v116
	v_add_f32_e32 v116, v92, v116
	v_add_f32_e32 v116, v93, v116
	v_cvt_pk_bf16_f32 v154, v88, v89
	v_cvt_pk_bf16_f32 v155, v90, v91
	s_waitcnt lgkmcnt(10)
	v_mfma_f32_32x32x16_bf16 v[36:51], v[120:123], v[160:163], v[36:51]
	ds_read_b64_tr_b16 v[88:89], v168 offset:25600
	ds_read_b64_tr_b16 v[90:91], v168 offset:26112
	s_waitcnt lgkmcnt(11)
	v_mfma_f32_32x32x16_bf16 v[68:83], v[104:107], v[156:159], v[68:83]
	v_add_f32_e32 v104, v94, v116
	v_add_f32_e32 v104, v95, v104
	v_add_f32_e32 v104, v96, v104
	v_add_f32_e32 v104, v97, v104
	v_cvt_pk_bf16_f32 v148, v92, v93
	v_cvt_pk_bf16_f32 v149, v94, v95
	ds_read_b64_tr_b16 v[92:93], v168 offset:29696
	ds_read_b64_tr_b16 v[94:95], v168 offset:30208
	v_add_f32_e32 v104, v98, v104
	v_add_f32_e32 v104, v99, v104
	v_add_f32_e32 v104, v52, v104
	v_add_f32_e32 v104, v53, v104
	v_cvt_pk_bf16_f32 v150, v96, v97
	v_cvt_pk_bf16_f32 v151, v98, v99
	s_waitcnt lgkmcnt(12)
	v_mfma_f32_32x32x16_bf16 v[36:51], v[124:127], v[156:159], v[36:51]
	ds_read_b64_tr_b16 v[96:97], v168 offset:26624
	ds_read_b64_tr_b16 v[98:99], v168 offset:27136
	v_add_f32_e32 v104, v54, v104
	v_add_f32_e32 v104, v55, v104
	v_add_f32_e32 v104, v56, v104
	v_add_f32_e32 v104, v57, v104
	v_cvt_pk_bf16_f32 v140, v52, v53
	v_cvt_pk_bf16_f32 v141, v54, v55
	s_waitcnt lgkmcnt(13)
	v_mfma_f32_32x32x16_bf16 v[68:83], v[108:111], v[144:147], v[68:83]
	ds_read_b64_tr_b16 v[52:53], v168 offset:30720
	ds_read_b64_tr_b16 v[54:55], v168 offset:31232
	v_add_f32_e32 v104, v58, v104
	v_add_f32_e32 v104, v59, v104
	v_add_f32_e32 v104, v60, v104
	v_add_f32_e32 v104, v61, v104
	v_cvt_pk_bf16_f32 v142, v56, v57
	v_cvt_pk_bf16_f32 v143, v58, v59
	s_waitcnt lgkmcnt(14)
	v_mfma_f32_32x32x16_bf16 v[36:51], v[128:131], v[144:147], v[36:51]
	ds_read_b64_tr_b16 v[56:57], v168 offset:27648
	ds_read_b64_tr_b16 v[58:59], v168 offset:28160
	v_add_f32_e32 v104, v62, v104
	v_add_f32_e32 v104, v63, v104
	v_add_f32_e32 v104, v64, v104
	v_add_f32_e32 v104, v65, v104
	v_cvt_pk_bf16_f32 v132, v60, v61
	v_cvt_pk_bf16_f32 v133, v62, v63
	s_waitcnt lgkmcnt(14)
	v_mfma_f32_32x32x16_bf16 v[68:83], v[112:115], v[136:139], v[68:83]
	ds_read_b64_tr_b16 v[60:61], v168 offset:31744
	ds_read_b64_tr_b16 v[62:63], v168 offset:32256
	v_mfma_f32_32x32x16_bf16 v[36:51], v[100:103], v[136:139], v[36:51]
	v_add_f32_e32 v100, v66, v104
	v_add_f32_e32 v100, v67, v100
	v_add_f32_e32 v100, 0, v100
	v_cvt_pk_bf16_f32 v134, v64, v65
	v_cvt_pk_bf16_f32 v135, v66, v67
	s_waitcnt lgkmcnt(14)
	v_mfma_f32_32x32x16_bf16 v[4:19], v[152:155], v[164:167], v[4:19]
	s_nop 1
	v_exp_f32_e32 v68, v68
	v_exp_f32_e32 v69, v69
	v_exp_f32_e32 v70, v70
	v_exp_f32_e32 v71, v71
	s_waitcnt lgkmcnt(12)
	v_mfma_f32_32x32x16_bf16 v[20:35], v[152:155], v[84:87], v[20:35]
	v_exp_f32_e32 v72, v72
	v_exp_f32_e32 v73, v73
	v_exp_f32_e32 v74, v74
	v_exp_f32_e32 v75, v75
	s_waitcnt lgkmcnt(10)
	v_mfma_f32_32x32x16_bf16 v[4:19], v[148:151], v[88:91], v[4:19]
	v_exp_f32_e32 v76, v76
	v_exp_f32_e32 v77, v77
	v_exp_f32_e32 v78, v78
	v_exp_f32_e32 v79, v79
	s_waitcnt lgkmcnt(8)
	v_mfma_f32_32x32x16_bf16 v[20:35], v[148:151], v[92:95], v[20:35]
	v_exp_f32_e32 v80, v80
	v_exp_f32_e32 v81, v81
	v_exp_f32_e32 v82, v82
	v_exp_f32_e32 v83, v83
	s_waitcnt lgkmcnt(6)
	v_mfma_f32_32x32x16_bf16 v[4:19], v[140:143], v[96:99], v[4:19]
	v_exp_f32_e32 v36, v36
	v_exp_f32_e32 v37, v37
	v_exp_f32_e32 v38, v38
	v_exp_f32_e32 v39, v39
	s_waitcnt lgkmcnt(4)
	v_mfma_f32_32x32x16_bf16 v[20:35], v[140:143], v[52:55], v[20:35]
	v_exp_f32_e32 v40, v40
	v_exp_f32_e32 v41, v41
	v_exp_f32_e32 v42, v42
	v_exp_f32_e32 v43, v43
	s_waitcnt lgkmcnt(2)
	v_mfma_f32_32x32x16_bf16 v[4:19], v[132:135], v[56:59], v[4:19]
	v_exp_f32_e32 v44, v44
	v_exp_f32_e32 v45, v45
	v_exp_f32_e32 v46, v46
	v_exp_f32_e32 v47, v47
	s_waitcnt lgkmcnt(0)
	v_mfma_f32_32x32x16_bf16 v[20:35], v[132:135], v[60:63], v[20:35]
	v_exp_f32_e32 v48, v48
	v_exp_f32_e32 v49, v49
	v_exp_f32_e32 v50, v50
	v_exp_f32_e32 v51, v51
	v_add_f32_e32 v52, v68, v69
	v_add_f32_e32 v52, v70, v52
	v_add_f32_e32 v52, v71, v52
	v_add_f32_e32 v52, v72, v52
	v_add_f32_e32 v52, v73, v52
	v_add_f32_e32 v52, v74, v52
	v_add_f32_e32 v52, v75, v52
	v_add_f32_e32 v52, v76, v52
	v_add_f32_e32 v52, v77, v52
	v_add_f32_e32 v52, v78, v52
	v_add_f32_e32 v52, v79, v52
	v_add_f32_e32 v52, v80, v52
	v_add_f32_e32 v52, v81, v52
	v_add_f32_e32 v52, v82, v52
	v_add_f32_e32 v52, v83, v52
	v_add_f32_e32 v52, v36, v52
	v_add_f32_e32 v52, v37, v52
	v_add_f32_e32 v52, v38, v52
	v_add_f32_e32 v52, v39, v52
	v_add_f32_e32 v52, v40, v52
	v_add_f32_e32 v52, v41, v52
	v_add_f32_e32 v52, v42, v52
	v_add_f32_e32 v52, v43, v52
	v_add_f32_e32 v52, v44, v52
	v_add_f32_e32 v52, v45, v52
	v_add_f32_e32 v52, v46, v52
	v_add_f32_e32 v52, v47, v52
	v_add_f32_e32 v52, v48, v52
	v_add_f32_e32 v52, v49, v52
	v_add_f32_e32 v52, v50, v52
	v_add_f32_e32 v52, v51, v52
	v_add_f32_e32 v1, v1, v100
	v_add_f32_e32 v1, v1, v52
	v_cvt_pk_bf16_f32 v52, v68, v69
	v_cvt_pk_bf16_f32 v53, v70, v71
	v_cvt_pk_bf16_f32 v54, v72, v73
	v_cvt_pk_bf16_f32 v55, v74, v75
	v_cvt_pk_bf16_f32 v56, v76, v77
	v_cvt_pk_bf16_f32 v57, v78, v79
	v_cvt_pk_bf16_f32 v58, v80, v81
	v_cvt_pk_bf16_f32 v59, v82, v83
	v_cvt_pk_bf16_f32 v36, v36, v37
	v_cvt_pk_bf16_f32 v37, v38, v39
	v_cvt_pk_bf16_f32 v38, v40, v41
	v_cvt_pk_bf16_f32 v39, v42, v43
	v_cvt_pk_bf16_f32 v40, v44, v45
	v_cvt_pk_bf16_f32 v41, v46, v47
	v_cvt_pk_bf16_f32 v42, v48, v49
	v_cvt_pk_bf16_f32 v43, v50, v51
	v_add3_u32 v0, v0, v3, s24
	ds_read_b64_tr_b16 v[44:45],v0 offset:0
	ds_read_b64_tr_b16 v[46:47],v0 offset:512
	ds_read_b64_tr_b16 v[48:49],v0 offset:1024
	ds_read_b64_tr_b16 v[50:51],v0 offset:1536
	ds_read_b64_tr_b16 v[60:61],v0 offset:2048
	ds_read_b64_tr_b16 v[62:63],v0 offset:2560
	ds_read_b64_tr_b16 v[64:65],v0 offset:3072
	ds_read_b64_tr_b16 v[66:67],v0 offset:3584
	s_waitcnt lgkmcnt(0)
	s_nop 0
	v_mfma_f32_32x32x16_bf16 v[4:19], v[52:55], v[44:47], v[4:19]
	ds_read_b64_tr_b16 v[44:45],v0 offset:4096
	ds_read_b64_tr_b16 v[46:47],v0 offset:4608
	v_mfma_f32_32x32x16_bf16 v[4:19], v[56:59], v[48:51], v[4:19]
	ds_read_b64_tr_b16 v[48:49],v0 offset:5120
	ds_read_b64_tr_b16 v[50:51],v0 offset:5632
	v_mfma_f32_32x32x16_bf16 v[4:19], v[36:39], v[60:63], v[4:19]
	ds_read_b64_tr_b16 v[60:61],v0 offset:6144
	ds_read_b64_tr_b16 v[62:63],v0 offset:6656
	v_mfma_f32_32x32x16_bf16 v[4:19], v[40:43], v[64:67], v[4:19]
	ds_read_b64_tr_b16 v[64:65],v0 offset:7168
	ds_read_b64_tr_b16 v[66:67],v0 offset:7680
	s_waitcnt lgkmcnt(0)
	v_mfma_f32_32x32x16_bf16 v[20:35], v[52:55], v[44:47], v[20:35]
	v_mfma_f32_32x32x16_bf16 v[20:35], v[56:59], v[48:51], v[20:35]
	v_mfma_f32_32x32x16_bf16 v[20:35], v[36:39], v[60:63], v[20:35]
	v_mfma_f32_32x32x16_bf16 v[20:35], v[40:43], v[64:67], v[20:35]
	s_setprio 0
	v_mov_b32_e32 v0, v1
	s_nop 1
	v_permlane32_swap_b32_e32 v1, v0
	v_cmp_gt_u32_e32 vcc, 32, v186
	s_and_saveexec_b64 s[24:25], vcc
	s_cbranch_execz .LBB0_727
	v_lshl_add_u32 v3, v188, 2, s28
	v_add_f32_e32 v0, v1, v0
	ds_write_b32 v3, v0 offset:49280
	s_branch .LBB0_727
